# XCD leader issues the release atomic before its own L1 invalidate (invalidate moved off the barrier release path) in all 8 barrier instances
# baseline (speedup 1.0000x reference)
.LBB0_238:
	s_or_b64 exec, exec, s[6:7]
	v_mov_b32_e32 v1, 0x2000
	v_mov_b32_e32 v2, 1
	s_waitcnt vmcnt(0)
	s_nop 0
	global_atomic_add v1, v2, s[4:5] offset:1024
	buffer_inv sc1
	s_waitcnt vmcnt(0)

.LBB0_483:
	s_or_b64 exec, exec, s[18:19]
	v_readlane_b32 s8, v254, 59
	v_readlane_b32 s9, v254, 60
	v_mov_b32_e32 v0, 1
	s_waitcnt vmcnt(0)
	s_nop 0
	s_nop 1
	global_atomic_add v1, v0, s[8:9]
	buffer_inv sc1
	s_waitcnt vmcnt(0)

.LBB0_704:
	s_or_b64 exec, exec, s[4:5]
	v_readlane_b32 s4, v254, 59
	v_readlane_b32 s5, v254, 60
	v_mov_b32_e32 v0, 1
	s_waitcnt vmcnt(0)
	s_nop 0
	s_nop 1
	global_atomic_add v1, v0, s[4:5]
	buffer_inv sc1
	s_waitcnt vmcnt(0)

.Lxcd_local_b:
	v_readlane_b32 s4, v254, 59
	v_readlane_b32 s5, v254, 60
	v_mov_b32_e32 v0, 1
	s_waitcnt vmcnt(0)
	s_nop 0
	s_nop 1
	global_atomic_add v1, v0, s[4:5]
	buffer_inv sc1
	s_waitcnt vmcnt(0)
